# grid barrier: the first workgroup of each XCD to arrive issues an early buffer_wbl2 so most dirty L2 lines are written back while the others finish (the last arriver's release write-back has less to f
# speedup vs baseline: 1.0092x; 1.0092x over previous
; __device__ __forceinline__ unsigned xb_ld(unsigned* p)              { return __hip_atomic_load(p, __ATOMIC_RELAXED, __HIP_MEMORY_SCOPE_AGENT); }
; __device__ __forceinline__ unsigned xb_add(unsigned* p, unsigned v) { return __hip_atomic_fetch_add(p, v, __ATOMIC_RELAXED, __HIP_MEMORY_SCOPE_AGENT); }
; #define XB_SPIN(cond, bar) do { unsigned _sp = 0; while (cond) { __builtin_amdgcn_s_sleep(1); \
;     if ((++_sp & 255u) == 0u) { if (xb_ld(&(bar)[XB_TMO])) break; if (_sp > XB_SPIN_CAP) { atomicAdd(&(bar)[XB_TMO], 1u); break; } } } } while (0)
; __device__ __forceinline__ void xcd_barrier(unsigned* bar, unsigned x, volatile LAS unsigned* st) {
;     ...
;         const unsigned old = xb_add(&bar[XB_XSUB(x)], 1u);
;         const unsigned gen = old / nloc;
;         if (old + 1u == (gen + 1u) * nloc) {
;             __builtin_amdgcn_fence(__ATOMIC_RELEASE, "agent");
;             asm volatile("s_waitcnt vmcnt(0)" ::: "memory");
;             const unsigned og = xb_add(&bar[XB_TOP], 1u);
;             const unsigned tg = og / nx;
;             if (og + 1u == (tg + 1u) * nx) xb_add(&bar[XB_TOPGEN], 1u);
;             else XB_SPIN(xb_ld(&bar[XB_TOPGEN]) == tg, bar);
;             __builtin_amdgcn_fence(__ATOMIC_ACQUIRE, "agent");
;             xb_add(&bar[XB_XGEN(x)], 1u);
;             asm volatile("s_waitcnt vmcnt(0)" ::: "memory");
;         } else {
;             XB_SPIN(xb_ld(&bar[XB_XGEN(x)]) == gen, bar);
.LBB0_864:
	s_or_b64 exec, exec, s[8:9]
	v_cvt_f32_u32_e32 v4, v2
	s_waitcnt vmcnt(0)
	v_readfirstlane_b32 s2, v3
	v_sub_u32_e32 v3, 0, v2
	v_rcp_iflag_f32_e32 v4, v4
	v_add_u32_e32 v5, s2, v1
	v_mul_f32_e32 v4, 0x4f7ffffe, v4
	v_cvt_u32_f32_e32 v4, v4
	v_mul_lo_u32 v1, v3, v4
	v_mul_hi_u32 v1, v4, v1
	v_add_u32_e32 v1, v4, v1
	v_mul_hi_u32 v1, v5, v1
	v_mul_lo_u32 v3, v1, v2
	v_sub_u32_e32 v3, v5, v3
	v_add_u32_e32 v4, 1, v1
	v_cmp_ge_u32_e32 vcc, v3, v2
	s_nop 1
	v_cndmask_b32_e32 v1, v1, v4, vcc
	v_sub_u32_e32 v4, v3, v2
	v_cndmask_b32_e32 v3, v3, v4, vcc
	v_add_u32_e32 v4, 1, v1
	v_cmp_ge_u32_e32 vcc, v3, v2
	v_add_u32_e32 v3, 1, v5
	s_nop 0
	v_cndmask_b32_e32 v1, v1, v4, vcc
	v_mul_lo_u32 v4, v2, v1
	v_add_u32_e32 v2, v4, v2
	v_cmp_ne_u32_e32 vcc, v3, v2
	s_and_saveexec_b64 s[2:3], vcc
	s_xor_b64 s[6:7], exec, s[2:3]
	s_cbranch_execz .LBB0_878
	v_cmp_eq_u32_e32 vcc, v5, v4
	s_cbranch_vccz .Lno_early_wb
	buffer_wbl2 sc1
.Lno_early_wb:
	s_waitcnt lgkmcnt(0)
	global_load_dword v0, v194, s[4:5] offset:1024 sc1
	s_add_u32 s10, s4, 0x2400
	s_addc_u32 s11, s5, 0
	s_waitcnt vmcnt(0)
	v_cmp_eq_u32_e32 vcc, v0, v1
	s_and_saveexec_b64 s[8:9], vcc
	s_cbranch_execz .LBB0_877
	s_mov_b32 s2, 0x40000
	global_load_dword v0, v33, s[10:11] sc1
